# rwkv loader: dead B/C (bb,cc) reductions and their LDS store replaced by s_nop now that the scan computes y = S_new.r directly
# speedup vs baseline: 1.0047x; 1.0047x over previous
.LBB0_1692:
	s_waitcnt vmcnt(5)
	v_lshlrev_b32_e32 v92, 16, v86
	v_and_b32_e32 v94, 0xffff0000, v86
	v_lshlrev_b32_e32 v30, 16, v28
	v_and_b32_e32 v31, 0xffff0000, v28
	v_lshlrev_b32_e32 v48, 16, v29
	v_and_b32_e32 v50, 0xffff0000, v29
	v_add_f32_e32 v28, -1.0, v92
	v_add_f32_e32 v29, -1.0, v94
	v_fma_f32 v97, v8, v28, 1.0
	v_mul_f32_e32 v28, 0xbfb8aa3b, v30
	v_fma_f32 v99, v9, v29, 1.0
	v_mul_f32_e32 v29, 0xbfb8aa3b, v31
	v_lshlrev_b32_e32 v30, 16, v34
	v_and_b32_e32 v31, 0xffff0000, v34
	v_lshlrev_b32_e32 v102, 16, v36
	v_and_b32_e32 v103, 0xffff0000, v36
	v_lshlrev_b32_e32 v100, 16, v32
	v_and_b32_e32 v101, 0xffff0000, v32
	v_pk_add_f32 v[30:31], v[30:31], v[102:103]
	v_lshlrev_b32_e32 v34, 16, v35
	v_and_b32_e32 v35, 0xffff0000, v35
	v_lshlrev_b32_e32 v36, 16, v37
	v_and_b32_e32 v37, 0xffff0000, v37
	v_pk_fma_f32 v[30:31], v[30:31], 0.5, v[100:101] op_sel_hi:[1,0,1] neg_lo:[0,0,1] neg_hi:[0,0,1]
	v_pk_add_f32 v[34:35], v[34:35], v[36:37]
	v_lshlrev_b32_e32 v36, 16, v78
	v_and_b32_e32 v37, 0xffff0000, v78
	v_lshlrev_b32_e32 v106, 16, v84
	v_and_b32_e32 v107, 0xffff0000, v84
	v_lshlrev_b32_e32 v78, 16, v79
	v_and_b32_e32 v79, 0xffff0000, v79
	v_lshlrev_b32_e32 v84, 16, v85
	v_and_b32_e32 v85, 0xffff0000, v85
	v_pk_fma_f32 v[100:101], v[24:25], v[30:31], v[100:101]
	v_lshlrev_b32_e32 v30, 16, v77
	v_lshlrev_b32_e32 v31, 16, v81
	v_pk_add_f32 v[36:37], v[36:37], v[106:107]
	v_pk_add_f32 v[78:79], v[78:79], v[84:85]
	v_lshlrev_b32_e32 v84, 16, v76
	v_and_b32_e32 v85, 0xffff0000, v76
	v_lshlrev_b32_e32 v106, 16, v80
	v_and_b32_e32 v107, 0xffff0000, v80
	v_add_f32_e32 v86, v31, v30
	v_and_b32_e32 v31, 0xffff0000, v81
	v_and_b32_e32 v32, 0xffff0000, v77
	v_lshlrev_b32_e32 v76, 16, v72
	v_and_b32_e32 v77, 0xffff0000, v72
	v_pk_add_f32 v[80:81], v[84:85], v[106:107]
	v_and_b32_e32 v88, 0xffff0000, v73
	v_mul_f32_e32 v30, 0xbfb8aa3b, v48
	v_add_f32_e32 v48, v31, v32
	v_pk_fma_f32 v[80:81], v[80:81], 0.5, v[76:77] op_sel_hi:[1,0,1] neg_lo:[0,0,1] neg_hi:[0,0,1]
	v_lshlrev_b32_e32 v104, 16, v38
	v_and_b32_e32 v105, 0xffff0000, v38
	v_lshlrev_b32_e32 v38, 16, v39
	v_and_b32_e32 v39, 0xffff0000, v39
	v_fma_f32 v48, v48, 0.5, -v88
	v_pk_fma_f32 v[76:77], v[16:17], v[80:81], v[76:77]
	v_and_b32_e32 v89, 0xffff0000, v87
	v_pk_fma_f32 v[78:79], v[78:79], 0.5, v[38:39] op_sel_hi:[1,0,1] neg_lo:[0,0,1] neg_hi:[0,0,1]
	v_mul_f32_e32 v48, v19, v48
	v_pk_mul_f32 v[80:81], v[12:13], v[76:77]
	v_mov_b32_e32 v93, v76
	v_lshlrev_b32_e32 v76, 16, v73
	v_pk_fma_f32 v[38:39], v[22:23], v[78:79], v[38:39]
	v_pk_add_f32 v[78:79], v[48:49], v[88:89]
	v_fma_f32 v48, v86, 0.5, -v76
	v_mov_b32_e32 v95, v77
	v_lshlrev_b32_e32 v77, 16, v87
	v_mul_f32_e32 v48, v18, v48
	v_pk_fma_f32 v[36:37], v[36:37], 0.5, v[104:105] op_sel_hi:[1,0,1] neg_lo:[0,0,1] neg_hi:[0,0,1]
	v_pk_add_f32 v[72:73], v[48:49], v[76:77]
	v_pk_fma_f32 v[36:37], v[20:21], v[36:37], v[104:105]
	v_pk_mul_f32 v[104:105], v[10:11], v[78:79]
	v_pk_mul_f32 v[86:87], v[14:15], v[72:73]
	v_pk_mul_f32 v[84:85], v[80:81], v[80:81]
	v_mov_b32_e32 v106, v104
	v_mov_b32_e32 v107, v86
	v_pk_mul_f32 v[106:107], v[106:107], v[106:107]
	v_add_f32_e32 v48, v84, v85
	v_add_f32_e32 v48, v107, v48
	v_add_f32_e32 v48, v106, v48
	v_mul_f32_e32 v31, 0xbfb8aa3b, v50
	s_bitcmp1_b32 s4, 0
	v_add_f32_dpp v48, v48, v48 quad_perm:[1,0,3,2] row_mask:0xf bank_mask:0xf bound_ctrl:1
	s_cselect_b32 s48, 0xc200, 0
	s_add_i32 s50, s48, 0
	v_add_f32_dpp v48, v48, v48 quad_perm:[2,3,0,1] row_mask:0xf bank_mask:0xf bound_ctrl:1
	v_lshlrev_b32_e32 v32, 16, v33
	v_and_b32_e32 v33, 0xffff0000, v33
	v_add_f32_dpp v48, v48, v48 row_half_mirror row_mask:0xf bank_mask:0xf bound_ctrl:1
	v_pk_fma_f32 v[34:35], v[34:35], 0.5, v[32:33] op_sel_hi:[1,0,1] neg_lo:[0,0,1] neg_hi:[0,0,1]
	v_exp_f32_e32 v28, v28
	v_add_f32_dpp v48, v48, v48 row_ror:8 row_mask:0xf bank_mask:0xf bound_ctrl:1
	v_cmp_gt_f32_e32 vcc, s96, v48
	v_mul_f32_e32 v50, 0x4f800000, v48
	v_pk_fma_f32 v[102:103], v[26:27], v[34:35], v[32:33]
	v_cndmask_b32_e32 v48, v48, v50, vcc
	v_sqrt_f32_e32 v50, v48
	v_exp_f32_e32 v29, v29
	v_exp_f32_e32 v30, v30
	v_exp_f32_e32 v31, v31
	v_add_u32_e32 v84, -1, v50
	v_fma_f32 v85, -v84, v50, v48
	v_cmp_ge_f32_e64 s[48:49], 0, v85
	v_add_u32_e32 v85, 1, v50
	v_pk_mul_f32 v[32:33], v[100:101], 1.0 op_sel_hi:[1,0]
	v_cndmask_b32_e64 v84, v50, v84, s[48:49]
	v_fma_f32 v50, -v85, v50, v48
	v_cmp_lt_f32_e64 s[48:49], 0, v50
	v_pk_mul_f32 v[34:35], v[102:103], 1.0 op_sel_hi:[1,0]
	s_nop 0
	v_cndmask_b32_e64 v50, v84, v85, s[48:49]
	v_mul_f32_e32 v84, 0x37800000, v50
	v_cndmask_b32_e32 v50, v50, v84, vcc
	v_cmp_class_f32_e32 vcc, v48, v191
	s_nop 1
	v_cndmask_b32_e32 v48, v50, v48, vcc
	v_max_f32_e32 v48, 0x2b8cbccc, v48
	v_div_scale_f32 v50, s[48:49], v48, v48, 1.0
	v_rcp_f32_e32 v84, v50
	s_nop 0
	v_fma_f32 v85, -v50, v84, 1.0
	v_fmac_f32_e32 v84, v85, v84
	v_div_scale_f32 v85, vcc, 1.0, v48, 1.0
	v_mul_f32_e32 v91, v85, v84
	v_fma_f32 v96, -v50, v91, v85
	v_fmac_f32_e32 v91, v96, v84
	v_fma_f32 v50, -v50, v91, v85
	v_div_fmas_f32 v50, v50, v84, v91
	v_div_fixup_f32 v50, v50, v48, 1.0
	v_pk_mul_f32 v[84:85], v[80:81], v[50:51] op_sel_hi:[1,0]
	v_pk_mul_f32 v[86:87], v[86:87], v[50:51]
	v_mov_b32_e32 v96, v84
	v_mov_b32_e32 v98, v85
	v_pk_mul_f32 v[80:81], v[96:97], v[92:93]
	v_pk_mul_f32 v[92:93], v[98:99], v[94:95]
	v_pk_fma_f32 v[94:95], v[14:15], v[72:73], s[84:85]
	v_mul_f32_e32 v48, v100, v81
	v_mov_b32_e32 v87, v95
	v_pk_mov_b32 v[72:73], v[76:77], v[72:73] op_sel:[1,0]
	v_fma_f32 v48, v4, v48, 0
	v_mul_f32_e32 v91, v101, v93
	v_pk_mul_f32 v[96:97], v[86:87], v[72:73]
	v_fmac_f32_e32 v48, v5, v91
	v_mul_f32_e32 v72, v102, v97
	v_fmac_f32_e32 v48, v6, v72
	v_pk_mul_f32 v[98:99], v[104:105], v[50:51]
	v_pk_fma_f32 v[72:73], v[10:11], v[78:79], s[84:85]
	s_nop 0
	v_mov_b32_e32 v99, v73
	v_pk_mov_b32 v[72:73], v[88:89], v[78:79] op_sel:[1,0]
	s_nop 0
	v_pk_mul_f32 v[94:95], v[98:99], v[72:73]
	s_nop 0
	s_nop 0
	v_mul_f32_e32 v50, v103, v95
	s_nop 0
	s_nop 0
	v_fmac_f32_e32 v48, v7, v50
	v_lshlrev_b32_e32 v78, 2, v46
	s_nop 0
	s_nop 0
	s_nop 0
	s_nop 0
	s_nop 0
	v_add_f32_dpp v48, v48, v48 quad_perm:[1,0,3,2] row_mask:0xf bank_mask:0xf bound_ctrl:1
	s_nop 0
	s_nop 0
	s_nop 0
	s_nop 0
	s_nop 0
	v_add_f32_dpp v48, v48, v48 quad_perm:[2,3,0,1] row_mask:0xf bank_mask:0xf bound_ctrl:1
	s_nop 0
	s_nop 0
	v_add_f32_dpp v48, v48, v48 row_half_mirror row_mask:0xf bank_mask:0xf bound_ctrl:1
	v_mov_b32_e32 v50, 0
	s_nop 0
	s_nop 0
	s_nop 0
	v_add3_u32 v79, s50, v166, v78
	v_mov_b32_dpp v50, v48 row_ror:8 row_mask:0xf bank_mask:0xf
	s_nop 0
	s_nop 0
	ds_write_b128 v79, v[28:31]
	v_mov_b32_e32 v87, v98
	v_mov_b32_e32 v28, v80
	v_mov_b32_e32 v29, v92
	v_mov_b32_e32 v30, v96
	v_mov_b32_e32 v31, v94
	v_mov_b32_e32 v92, v81
	v_mov_b32_e32 v94, v97
	ds_write_b128 v79, v[84:87] offset:8192
	ds_write_b128 v79, v[28:31] offset:16384
	ds_write_b128 v79, v[92:95] offset:24576
	ds_write_b128 v79, v[32:35] offset:32768
	ds_write_b128 v79, v[36:39] offset:40960
	s_nop 0
	s_nop 0
	s_nop 0
	s_nop 0
	s_nop 0
	v_add_u32_e32 v76, s56, v158
	v_cmp_lt_i32_e32 vcc, s67, v76
	s_and_b64 s[92:93], s[46:47], vcc
	s_and_saveexec_b64 s[48:49], s[92:93]
	s_cbranch_execz .LBB0_1696
	v_add_u32_e32 v28, 0xffffff00, v76
	v_cndmask_b32_e32 v30, v171, v172, vcc
	v_cndmask_b32_e32 v31, v76, v28, vcc
	v_mov_b32_e32 v28, s87
	v_mov_b32_e32 v29, s91
	v_add_u32_e32 v30, v30, v90
	v_cndmask_b32_e32 v29, v28, v29, vcc
	v_mov_b32_e32 v28, s86
	v_mov_b32_e32 v32, s90
	v_cndmask_b32_e64 v30, v30, v31, s[44:45]
	v_cndmask_b32_e32 v28, v28, v32, vcc
	v_ashrrev_i32_e32 v31, 31, v30
	v_lshl_add_u64 v[28:29], v[28:29], 0, v[30:31]
	v_lshlrev_b64 v[28:29], 7, v[28:29]
	v_add_f32_e32 v30, v48, v50
	v_lshl_add_u64 v[28:29], s[88:89], 0, v[28:29]
	global_store_dword v[28:29], v30, off
.LBB0_1696:
	s_or_b64 exec, exec, s[48:49]
	s_waitcnt vmcnt(0)
	v_lshlrev_b32_e32 v80, 16, v70
	v_lshlrev_b32_e32 v28, 16, v82
	v_and_b32_e32 v29, 0xffff0000, v82
	v_and_b32_e32 v82, 0xffff0000, v70
	v_add_f32_e32 v30, -1.0, v80
	v_fma_f32 v85, v8, v30, 1.0
	v_add_f32_e32 v30, -1.0, v82
	v_fma_f32 v87, v9, v30, 1.0
	v_lshlrev_b32_e32 v30, 16, v66
	v_and_b32_e32 v31, 0xffff0000, v66
	v_lshlrev_b32_e32 v34, 16, v74
	v_and_b32_e32 v35, 0xffff0000, v74
	v_lshlrev_b32_e32 v32, 16, v60
	v_and_b32_e32 v33, 0xffff0000, v60
	v_pk_add_f32 v[30:31], v[30:31], v[34:35]
	v_lshlrev_b32_e32 v36, 16, v83
	v_pk_fma_f32 v[30:31], v[30:31], 0.5, v[32:33] op_sel_hi:[1,0,1] neg_lo:[0,0,1] neg_hi:[0,0,1]
	v_and_b32_e32 v37, 0xffff0000, v83
	v_pk_fma_f32 v[88:89], v[24:25], v[30:31], v[32:33]
	v_lshlrev_b32_e32 v30, 16, v55
	v_lshlrev_b32_e32 v31, 16, v65
	v_add_f32_e32 v50, v31, v30
	v_and_b32_e32 v31, 0xffff0000, v65
	v_and_b32_e32 v32, 0xffff0000, v55
	v_mul_f32_e32 v30, 0xbfb8aa3b, v36
	v_add_f32_e32 v48, v31, v32
	v_mul_f32_e32 v31, 0xbfb8aa3b, v37
	v_lshlrev_b32_e32 v32, 16, v67
	v_and_b32_e32 v33, 0xffff0000, v67
	v_lshlrev_b32_e32 v36, 16, v75
	v_and_b32_e32 v37, 0xffff0000, v75
	v_pk_add_f32 v[32:33], v[32:33], v[36:37]
	v_lshlrev_b32_e32 v36, 16, v58
	v_and_b32_e32 v37, 0xffff0000, v58
	v_lshlrev_b32_e32 v66, 16, v68
	v_and_b32_e32 v67, 0xffff0000, v68
	v_lshlrev_b32_e32 v38, 16, v56
	v_and_b32_e32 v39, 0xffff0000, v56
	v_pk_add_f32 v[36:37], v[36:37], v[66:67]
	v_lshlrev_b32_e32 v58, 16, v69
	v_pk_fma_f32 v[36:37], v[36:37], 0.5, v[38:39] op_sel_hi:[1,0,1] neg_lo:[0,0,1] neg_hi:[0,0,1]
	v_lshlrev_b32_e32 v56, 16, v57
	v_pk_fma_f32 v[36:37], v[20:21], v[36:37], v[38:39]
	v_lshlrev_b32_e32 v38, 16, v59
	v_and_b32_e32 v39, 0xffff0000, v59
	v_and_b32_e32 v59, 0xffff0000, v69
	v_and_b32_e32 v57, 0xffff0000, v57
	v_pk_add_f32 v[38:39], v[38:39], v[58:59]
	v_lshlrev_b32_e32 v58, 16, v64
	v_pk_fma_f32 v[38:39], v[38:39], 0.5, v[56:57] op_sel_hi:[1,0,1] neg_lo:[0,0,1] neg_hi:[0,0,1]
	v_and_b32_e32 v59, 0xffff0000, v64
	v_pk_fma_f32 v[38:39], v[22:23], v[38:39], v[56:57]
	v_lshlrev_b32_e32 v56, 16, v54
	v_and_b32_e32 v57, 0xffff0000, v54
	v_lshlrev_b32_e32 v54, 16, v52
	v_and_b32_e32 v55, 0xffff0000, v52
	v_pk_add_f32 v[56:57], v[56:57], v[58:59]
	v_and_b32_e32 v72, 0xffff0000, v53
	v_pk_fma_f32 v[56:57], v[56:57], 0.5, v[54:55] op_sel_hi:[1,0,1] neg_lo:[0,0,1] neg_hi:[0,0,1]
	v_fma_f32 v48, v48, 0.5, -v72
	v_pk_fma_f32 v[54:55], v[16:17], v[56:57], v[54:55]
	v_and_b32_e32 v73, 0xffff0000, v71
	v_mul_f32_e32 v48, v19, v48
	v_pk_mul_f32 v[56:57], v[12:13], v[54:55]
	v_mov_b32_e32 v81, v54
	v_lshlrev_b32_e32 v54, 16, v53
	v_pk_add_f32 v[66:67], v[48:49], v[72:73]
	v_fma_f32 v48, v50, 0.5, -v54
	v_mov_b32_e32 v83, v55
	v_lshlrev_b32_e32 v55, 16, v71
	v_mul_f32_e32 v48, v18, v48
	v_pk_add_f32 v[52:53], v[48:49], v[54:55]
	v_pk_mul_f32 v[68:69], v[10:11], v[66:67]
	v_pk_mul_f32 v[70:71], v[14:15], v[52:53]
	v_pk_mul_f32 v[58:59], v[56:57], v[56:57]
	v_mov_b32_e32 v64, v68
	v_mov_b32_e32 v65, v70
	v_pk_mul_f32 v[64:65], v[64:65], v[64:65]
	v_add_f32_e32 v48, v58, v59
	v_add_f32_e32 v48, v65, v48
	v_add_f32_e32 v48, v64, v48
	v_lshlrev_b32_e32 v34, 16, v61
	v_and_b32_e32 v35, 0xffff0000, v61
	v_add_f32_dpp v48, v48, v48 quad_perm:[1,0,3,2] row_mask:0xf bank_mask:0xf bound_ctrl:1
	v_pk_fma_f32 v[32:33], v[32:33], 0.5, v[34:35] op_sel_hi:[1,0,1] neg_lo:[0,0,1] neg_hi:[0,0,1]
	v_mul_f32_e32 v28, 0xbfb8aa3b, v28
	v_add_f32_dpp v48, v48, v48 quad_perm:[2,3,0,1] row_mask:0xf bank_mask:0xf bound_ctrl:1
	v_pk_fma_f32 v[60:61], v[26:27], v[32:33], v[34:35]
	v_mul_f32_e32 v29, 0xbfb8aa3b, v29
	v_add_f32_dpp v48, v48, v48 row_half_mirror row_mask:0xf bank_mask:0xf bound_ctrl:1
	v_exp_f32_e32 v30, v30
	v_exp_f32_e32 v31, v31
	v_add_f32_dpp v48, v48, v48 row_ror:8 row_mask:0xf bank_mask:0xf bound_ctrl:1
	v_cmp_gt_f32_e32 vcc, s96, v48
	v_mul_f32_e32 v50, 0x4f800000, v48
	v_exp_f32_e32 v28, v28
	v_cndmask_b32_e32 v48, v48, v50, vcc
	v_sqrt_f32_e32 v50, v48
	v_exp_f32_e32 v29, v29
	v_pk_mul_f32 v[34:35], v[60:61], 1.0 op_sel_hi:[1,0]
	v_add_u32_e32 v58, -1, v50
	v_fma_f32 v59, -v58, v50, v48
	v_cmp_ge_f32_e64 s[48:49], 0, v59
	v_add_u32_e32 v59, 1, v50
	v_pk_mul_f32 v[32:33], v[88:89], 1.0 op_sel_hi:[1,0]
	v_cndmask_b32_e64 v58, v50, v58, s[48:49]
	v_fma_f32 v50, -v59, v50, v48
	v_cmp_lt_f32_e64 s[48:49], 0, v50
	s_nop 1
	v_cndmask_b32_e64 v50, v58, v59, s[48:49]
	v_mul_f32_e32 v58, 0x37800000, v50
	v_cndmask_b32_e32 v50, v50, v58, vcc
	v_cmp_class_f32_e32 vcc, v48, v191
	s_nop 1
	v_cndmask_b32_e32 v48, v50, v48, vcc
	v_max_f32_e32 v48, 0x2b8cbccc, v48
	v_div_scale_f32 v50, s[48:49], v48, v48, 1.0
	v_rcp_f32_e32 v58, v50
	s_nop 0
	v_fma_f32 v59, -v50, v58, 1.0
	v_fmac_f32_e32 v58, v59, v58
	v_div_scale_f32 v59, vcc, 1.0, v48, 1.0
	v_mul_f32_e32 v64, v59, v58
	v_fma_f32 v65, -v50, v64, v59
	v_fmac_f32_e32 v64, v65, v58
	v_fma_f32 v50, -v50, v64, v59
	v_div_fmas_f32 v50, v50, v58, v64
	v_div_fixup_f32 v50, v50, v48, 1.0
	v_pk_mul_f32 v[56:57], v[56:57], v[50:51] op_sel_hi:[1,0]
	v_pk_mul_f32 v[68:69], v[68:69], v[50:51]
	v_mov_b32_e32 v84, v56
	v_pk_mul_f32 v[74:75], v[84:85], v[80:81]
	v_mov_b32_e32 v86, v57
	v_mul_f32_e32 v48, v88, v75
	v_pk_mul_f32 v[64:65], v[86:87], v[82:83]
	v_fma_f32 v48, v4, v48, 0
	v_mul_f32_e32 v58, v89, v65
	v_fmac_f32_e32 v48, v5, v58
	v_pk_mul_f32 v[58:59], v[70:71], v[50:51]
	v_pk_fma_f32 v[70:71], v[14:15], v[52:53], s[84:85]
	v_pk_mov_b32 v[52:53], v[54:55], v[52:53] op_sel:[1,0]
	v_mov_b32_e32 v59, v71
	v_pk_mul_f32 v[70:71], v[58:59], v[52:53]
	s_nop 0
	v_mul_f32_e32 v52, v60, v71
	v_fmac_f32_e32 v48, v6, v52
	v_pk_fma_f32 v[52:53], v[10:11], v[66:67], s[84:85]
	s_nop 0
	v_mov_b32_e32 v69, v53
	v_pk_mov_b32 v[52:53], v[72:73], v[66:67] op_sel:[1,0]
	v_mov_b32_e32 v59, v68
	v_pk_mul_f32 v[66:67], v[68:69], v[52:53]
	s_nop 0
	s_nop 0
	v_mul_f32_e32 v50, v61, v67
	s_nop 0
	s_nop 0
	v_fmac_f32_e32 v48, v7, v50
	v_mov_b32_e32 v50, 0
	s_nop 0
	s_nop 0
	s_nop 0
	s_nop 0
	s_nop 0
	v_add_f32_dpp v48, v48, v48 quad_perm:[1,0,3,2] row_mask:0xf bank_mask:0xf bound_ctrl:1
	s_nop 0
	s_nop 0
	s_nop 0
	s_nop 0
	s_nop 0
	v_add_f32_dpp v48, v48, v48 quad_perm:[2,3,0,1] row_mask:0xf bank_mask:0xf bound_ctrl:1
	s_nop 0
	s_nop 0
	v_add_f32_dpp v48, v48, v48 row_half_mirror row_mask:0xf bank_mask:0xf bound_ctrl:1
	s_nop 0
	s_nop 0
	s_nop 0
	v_add3_u32 v60, s50, v168, v78
	v_mov_b32_dpp v50, v48 row_ror:8 row_mask:0xf bank_mask:0xf
	s_nop 0
	s_nop 0
	ds_write_b128 v60, v[28:31]
	v_mov_b32_e32 v28, v74
	v_mov_b32_e32 v29, v64
	v_mov_b32_e32 v30, v70
	v_mov_b32_e32 v31, v66
	v_mov_b32_e32 v64, v75
	v_mov_b32_e32 v66, v71
	ds_write_b128 v60, v[56:59] offset:8192
	ds_write_b128 v60, v[28:31] offset:16384
	ds_write_b128 v60, v[64:67] offset:24576
	ds_write_b128 v60, v[32:35] offset:32768
	ds_write_b128 v60, v[36:39] offset:40960
	s_nop 0
	s_nop 0
	s_nop 0
	s_nop 0
	s_nop 0
	v_cmp_lt_i32_e32 vcc, s70, v76
	s_and_b64 s[50:51], s[46:47], vcc
	s_and_saveexec_b64 s[48:49], s[50:51]
	s_cbranch_execz .LBB0_1700
	v_cndmask_b32_e32 v30, 16, v178, vcc
	v_cndmask_b32_e32 v31, v179, v180, vcc
	v_mov_b32_e32 v28, s87
	v_mov_b32_e32 v29, s91
	v_add3_u32 v30, v158, v30, s56
	v_add_u32_e32 v31, v31, v90
	v_cndmask_b32_e32 v29, v28, v29, vcc
	v_mov_b32_e32 v28, s86
	v_mov_b32_e32 v32, s90
	v_cndmask_b32_e64 v30, v31, v30, s[44:45]
	v_cndmask_b32_e32 v28, v28, v32, vcc
	v_ashrrev_i32_e32 v31, 31, v30
	v_lshl_add_u64 v[28:29], v[28:29], 0, v[30:31]
	v_lshlrev_b64 v[28:29], 7, v[28:29]
	v_add_f32_e32 v30, v48, v50
	v_lshl_add_u64 v[28:29], s[88:89], 0, v[28:29]
	global_store_dword v[28:29], v30, off

.LBB0_1718:
	s_waitcnt vmcnt(5)
	v_lshlrev_b32_e32 v88, 16, v86
	v_and_b32_e32 v90, 0xffff0000, v86
	v_lshlrev_b32_e32 v30, 16, v28
	v_and_b32_e32 v31, 0xffff0000, v28
	v_lshlrev_b32_e32 v40, 16, v29
	v_and_b32_e32 v48, 0xffff0000, v29
	v_add_f32_e32 v28, -1.0, v88
	v_add_f32_e32 v29, -1.0, v90
	v_fma_f32 v93, v8, v28, 1.0
	v_mul_f32_e32 v28, 0xbfb8aa3b, v30
	v_fma_f32 v95, v9, v29, 1.0
	v_mul_f32_e32 v29, 0xbfb8aa3b, v31
	v_lshlrev_b32_e32 v30, 16, v34
	v_and_b32_e32 v31, 0xffff0000, v34
	v_lshlrev_b32_e32 v98, 16, v36
	v_and_b32_e32 v99, 0xffff0000, v36
	v_lshlrev_b32_e32 v96, 16, v32
	v_and_b32_e32 v97, 0xffff0000, v32
	v_pk_add_f32 v[30:31], v[30:31], v[98:99]
	v_lshlrev_b32_e32 v34, 16, v35
	v_pk_fma_f32 v[30:31], v[30:31], 0.5, v[96:97] op_sel_hi:[1,0,1] neg_lo:[0,0,1] neg_hi:[0,0,1]
	v_and_b32_e32 v35, 0xffff0000, v35
	v_lshlrev_b32_e32 v36, 16, v37
	v_and_b32_e32 v37, 0xffff0000, v37
	v_pk_fma_f32 v[96:97], v[24:25], v[30:31], v[96:97]
	v_lshlrev_b32_e32 v30, 16, v77
	v_lshlrev_b32_e32 v31, 16, v81
	v_pk_add_f32 v[34:35], v[34:35], v[36:37]
	v_lshlrev_b32_e32 v36, 16, v78
	v_and_b32_e32 v37, 0xffff0000, v78
	v_lshlrev_b32_e32 v102, 16, v84
	v_and_b32_e32 v103, 0xffff0000, v84
	v_lshlrev_b32_e32 v78, 16, v79
	v_and_b32_e32 v79, 0xffff0000, v79
	v_lshlrev_b32_e32 v84, 16, v85
	v_and_b32_e32 v85, 0xffff0000, v85
	v_add_f32_e32 v50, v31, v30
	v_and_b32_e32 v31, 0xffff0000, v81
	v_and_b32_e32 v32, 0xffff0000, v77
	v_lshlrev_b32_e32 v100, 16, v38
	v_and_b32_e32 v101, 0xffff0000, v38
	v_lshlrev_b32_e32 v38, 16, v39
	v_and_b32_e32 v39, 0xffff0000, v39
	v_pk_add_f32 v[78:79], v[78:79], v[84:85]
	v_and_b32_e32 v62, 0xffff0000, v73
	v_mul_f32_e32 v30, 0xbfb8aa3b, v40
	v_add_f32_e32 v40, v31, v32
	v_pk_fma_f32 v[78:79], v[78:79], 0.5, v[38:39] op_sel_hi:[1,0,1] neg_lo:[0,0,1] neg_hi:[0,0,1]
	v_pk_add_f32 v[36:37], v[36:37], v[102:103]
	v_pk_fma_f32 v[38:39], v[22:23], v[78:79], v[38:39]
	v_fma_f32 v40, v40, 0.5, -v62
	v_lshlrev_b32_e32 v78, 16, v76
	v_and_b32_e32 v79, 0xffff0000, v76
	v_lshlrev_b32_e32 v84, 16, v80
	v_and_b32_e32 v85, 0xffff0000, v80
	v_lshlrev_b32_e32 v86, 16, v73
	v_and_b32_e32 v63, 0xffff0000, v87
	v_mul_f32_e32 v31, 0xbfb8aa3b, v48
	v_pk_fma_f32 v[36:37], v[36:37], 0.5, v[100:101] op_sel_hi:[1,0,1] neg_lo:[0,0,1] neg_hi:[0,0,1]
	v_mul_f32_e32 v48, v19, v40
	v_lshlrev_b32_e32 v76, 16, v72
	v_and_b32_e32 v77, 0xffff0000, v72
	v_pk_add_f32 v[78:79], v[78:79], v[84:85]
	v_fma_f32 v40, v50, 0.5, -v86
	v_pk_fma_f32 v[36:37], v[20:21], v[36:37], v[100:101]
	v_pk_add_f32 v[100:101], v[48:49], v[62:63]
	v_pk_fma_f32 v[78:79], v[78:79], 0.5, v[76:77] op_sel_hi:[1,0,1] neg_lo:[0,0,1] neg_hi:[0,0,1]
	v_lshlrev_b32_e32 v87, 16, v87
	v_mul_f32_e32 v48, v18, v40
	v_pk_fma_f32 v[76:77], v[16:17], v[78:79], v[76:77]
	v_pk_add_f32 v[72:73], v[48:49], v[86:87]
	v_pk_mul_f32 v[102:103], v[10:11], v[100:101]
	v_pk_mul_f32 v[78:79], v[12:13], v[76:77]
	v_pk_mul_f32 v[104:105], v[14:15], v[72:73]
	v_pk_mul_f32 v[80:81], v[78:79], v[78:79]
	v_mov_b32_e32 v89, v76
	v_mov_b32_e32 v91, v77
	v_mov_b32_e32 v76, v102
	v_mov_b32_e32 v77, v104
	v_pk_mul_f32 v[76:77], v[76:77], v[76:77]
	v_add_f32_e32 v40, v80, v81
	v_add_f32_e32 v40, v77, v40
	v_add_f32_e32 v40, v76, v40
	v_lshlrev_b32_e32 v32, 16, v33
	v_and_b32_e32 v33, 0xffff0000, v33
	v_add_f32_dpp v40, v40, v40 quad_perm:[1,0,3,2] row_mask:0xf bank_mask:0xf bound_ctrl:1
	v_pk_mov_b32 v[62:63], v[62:63], v[100:101] op_sel:[1,0]
	v_pk_fma_f32 v[34:35], v[34:35], 0.5, v[32:33] op_sel_hi:[1,0,1] neg_lo:[0,0,1] neg_hi:[0,0,1]
	v_add_f32_dpp v40, v40, v40 quad_perm:[2,3,0,1] row_mask:0xf bank_mask:0xf bound_ctrl:1
	v_pk_fma_f32 v[98:99], v[26:27], v[34:35], v[32:33]
	v_exp_f32_e32 v28, v28
	v_add_f32_dpp v40, v40, v40 row_half_mirror row_mask:0xf bank_mask:0xf bound_ctrl:1
	v_exp_f32_e32 v29, v29
	v_exp_f32_e32 v30, v30
	v_add_f32_dpp v40, v40, v40 row_ror:8 row_mask:0xf bank_mask:0xf bound_ctrl:1
	v_cmp_gt_f32_e32 vcc, s96, v40
	v_mul_f32_e32 v48, 0x4f800000, v40
	v_exp_f32_e32 v31, v31
	v_cndmask_b32_e32 v40, v40, v48, vcc
	v_sqrt_f32_e32 v48, v40
	v_pk_mul_f32 v[32:33], v[96:97], 1.0 op_sel_hi:[1,0]
	v_pk_mul_f32 v[34:35], v[98:99], 1.0 op_sel_hi:[1,0]
	ds_write_b128 v175, v[28:31] offset:49664
	v_add_u32_e32 v50, -1, v48
	v_fma_f32 v76, -v50, v48, v40
	v_cmp_ge_f32_e64 s[48:49], 0, v76
	v_add_u32_e32 v76, 1, v48
	s_nop 0
	v_cndmask_b32_e64 v50, v48, v50, s[48:49]
	v_fma_f32 v48, -v76, v48, v40
	v_cmp_lt_f32_e64 s[48:49], 0, v48
	s_nop 1
	v_cndmask_b32_e64 v48, v50, v76, s[48:49]
	v_mul_f32_e32 v50, 0x37800000, v48
	v_cndmask_b32_e32 v48, v48, v50, vcc
	v_cmp_class_f32_e32 vcc, v40, v191
	s_nop 1
	v_cndmask_b32_e32 v40, v48, v40, vcc
	v_max_f32_e32 v40, 0x2b8cbccc, v40
	v_div_scale_f32 v48, s[4:5], v40, v40, 1.0
	v_rcp_f32_e32 v50, v48
	s_nop 0
	v_fma_f32 v76, -v48, v50, 1.0
	v_fmac_f32_e32 v50, v76, v50
	v_div_scale_f32 v76, vcc, 1.0, v40, 1.0
	v_mul_f32_e32 v77, v76, v50
	v_fma_f32 v80, -v48, v77, v76
	v_fmac_f32_e32 v77, v80, v50
	v_fma_f32 v48, -v48, v77, v76
	v_div_fmas_f32 v48, v48, v50, v77
	v_div_fixup_f32 v50, v48, v40, 1.0
	v_pk_mul_f32 v[76:77], v[78:79], v[50:51] op_sel_hi:[1,0]
	v_pk_mul_f32 v[78:79], v[104:105], v[50:51]
	v_mov_b32_e32 v92, v76
	v_pk_mul_f32 v[80:81], v[92:93], v[88:89]
	v_pk_fma_f32 v[88:89], v[14:15], v[72:73], s[84:85]
	v_mov_b32_e32 v94, v77
	v_mov_b32_e32 v79, v89
	v_pk_mov_b32 v[72:73], v[86:87], v[72:73] op_sel:[1,0]
	v_pk_mul_f32 v[84:85], v[94:95], v[90:91]
	v_pk_mul_f32 v[88:89], v[78:79], v[72:73]
	v_pk_mul_f32 v[90:91], v[102:103], v[50:51]
	v_pk_fma_f32 v[72:73], v[10:11], v[100:101], s[84:85]
	v_mul_f32_e32 v40, v96, v81
	v_mov_b32_e32 v91, v73
	v_pk_mul_f32 v[86:87], v[90:91], v[62:63]
	s_nop 0
	s_nop 0
	v_fma_f32 v40, v4, v40, 0
	s_nop 0
	v_mul_f32_e32 v48, v97, v85
	s_nop 0
	s_nop 0
	s_nop 0
	v_fmac_f32_e32 v40, v5, v48
	v_mul_f32_e32 v48, v98, v89
	s_nop 0
	s_nop 0
	v_fmac_f32_e32 v40, v6, v48
	v_mul_f32_e32 v48, v99, v87
	s_nop 0
	s_nop 0
	s_nop 0
	v_fmac_f32_e32 v40, v7, v48
	s_nop 0
	s_nop 0
	v_add_f32_dpp v40, v40, v40 quad_perm:[1,0,3,2] row_mask:0xf bank_mask:0xf bound_ctrl:1
	s_nop 0
	s_nop 0
	s_nop 0
	v_add_f32_dpp v40, v40, v40 quad_perm:[2,3,0,1] row_mask:0xf bank_mask:0xf bound_ctrl:1
	s_nop 0
	s_nop 0
	v_add_f32_dpp v40, v40, v40 row_half_mirror row_mask:0xf bank_mask:0xf bound_ctrl:1
	v_mov_b32_e32 v48, v41
	s_nop 0
	s_nop 0
	s_nop 0
	v_mov_b32_dpp v48, v40 row_ror:8 row_mask:0xf bank_mask:0xf
	s_nop 0
	s_nop 0
	v_mov_b32_e32 v79, v90
	v_mov_b32_e32 v28, v80
	v_mov_b32_e32 v29, v84
	v_mov_b32_e32 v30, v88
	v_mov_b32_e32 v31, v86
	v_mov_b32_e32 v84, v81
	v_mov_b32_e32 v86, v89
	ds_write_b128 v175, v[76:79] offset:57856
	ds_write_b128 v176, v[28:31] offset:16384
	ds_write_b128 v176, v[84:87] offset:24576
	ds_write_b128 v176, v[32:35] offset:32768
	ds_write_b128 v176, v[36:39] offset:40960
	s_nop 0
	s_nop 0
	s_nop 0
	s_nop 0
	s_and_b64 s[4:5], s[46:47], s[40:41]
	s_and_saveexec_b64 s[48:49], s[4:5]
	s_cbranch_execz .LBB0_1722
	v_mov_b32_e32 v28, s87
	v_mov_b32_e32 v29, s91
	v_cndmask_b32_e64 v29, v28, v29, s[40:41]
	v_mov_b32_e32 v28, s86
	v_mov_b32_e32 v30, s90
	v_cndmask_b32_e64 v28, v28, v30, s[40:41]
	v_cndmask_b32_e64 v30, v174, v173, s[44:45]
	v_ashrrev_i32_e32 v31, 31, v30
	v_lshl_add_u64 v[28:29], v[28:29], 0, v[30:31]
	v_lshlrev_b64 v[28:29], 7, v[28:29]
	v_add_f32_e32 v30, v40, v48
	v_lshl_add_u64 v[28:29], s[88:89], 0, v[28:29]
	global_store_dword v[28:29], v30, off
.LBB0_1722:
	s_or_b64 exec, exec, s[48:49]
	s_waitcnt vmcnt(0)
	v_lshlrev_b32_e32 v34, 16, v70
	v_lshlrev_b32_e32 v28, 16, v82
	v_add_f32_e32 v30, -1.0, v34
	v_and_b32_e32 v36, 0xffff0000, v70
	v_fma_f32 v39, v8, v30, 1.0
	v_mul_f32_e32 v8, 0xbfb8aa3b, v28
	v_lshlrev_b32_e32 v30, 16, v66
	v_and_b32_e32 v31, 0xffff0000, v66
	v_lshlrev_b32_e32 v72, 16, v74
	v_and_b32_e32 v73, 0xffff0000, v74
	v_and_b32_e32 v29, 0xffff0000, v82
	v_exp_f32_e32 v28, v8
	v_add_f32_e32 v8, -1.0, v36
	v_lshlrev_b32_e32 v62, 16, v60
	v_and_b32_e32 v63, 0xffff0000, v60
	v_pk_add_f32 v[30:31], v[30:31], v[72:73]
	v_fma_f32 v9, v9, v8, 1.0
	v_mul_f32_e32 v8, 0xbfb8aa3b, v29
	v_pk_fma_f32 v[30:31], v[30:31], 0.5, v[62:63] op_sel_hi:[1,0,1] neg_lo:[0,0,1] neg_hi:[0,0,1]
	v_lshlrev_b32_e32 v35, 16, v83
	v_exp_f32_e32 v29, v8
	v_pk_fma_f32 v[62:63], v[24:25], v[30:31], v[62:63]
	v_lshlrev_b32_e32 v8, 16, v55
	v_lshlrev_b32_e32 v24, 16, v65
	v_add_f32_e32 v8, v24, v8
	v_mul_f32_e32 v24, 0xbfb8aa3b, v35
	v_and_b32_e32 v37, 0xffff0000, v83
	v_exp_f32_e32 v30, v24
	v_and_b32_e32 v24, 0xffff0000, v65
	v_and_b32_e32 v25, 0xffff0000, v55
	v_add_f32_e32 v35, v24, v25
	v_mul_f32_e32 v24, 0xbfb8aa3b, v37
	v_exp_f32_e32 v31, v24
	v_lshlrev_b32_e32 v24, 16, v67
	v_and_b32_e32 v25, 0xffff0000, v67
	v_lshlrev_b32_e32 v66, 16, v75
	v_and_b32_e32 v67, 0xffff0000, v75
	v_pk_add_f32 v[24:25], v[24:25], v[66:67]
	v_lshlrev_b32_e32 v66, 16, v58
	v_and_b32_e32 v67, 0xffff0000, v58
	v_lshlrev_b32_e32 v74, 16, v68
	v_and_b32_e32 v75, 0xffff0000, v68
	v_lshlrev_b32_e32 v72, 16, v56
	v_and_b32_e32 v73, 0xffff0000, v56
	v_pk_add_f32 v[66:67], v[66:67], v[74:75]
	v_lshlrev_b32_e32 v58, 16, v59
	v_pk_fma_f32 v[66:67], v[66:67], 0.5, v[72:73] op_sel_hi:[1,0,1] neg_lo:[0,0,1] neg_hi:[0,0,1]
	v_and_b32_e32 v59, 0xffff0000, v59
	v_pk_fma_f32 v[20:21], v[20:21], v[66:67], v[72:73]
	v_lshlrev_b32_e32 v66, 16, v69
	v_and_b32_e32 v67, 0xffff0000, v69
	v_pk_add_f32 v[58:59], v[58:59], v[66:67]
	v_lshlrev_b32_e32 v66, 16, v54
	v_and_b32_e32 v67, 0xffff0000, v54
	v_lshlrev_b32_e32 v68, 16, v64
	v_and_b32_e32 v69, 0xffff0000, v64
	v_lshlrev_b32_e32 v54, 16, v52
	v_and_b32_e32 v55, 0xffff0000, v52
	v_pk_add_f32 v[64:65], v[66:67], v[68:69]
	v_and_b32_e32 v32, 0xffff0000, v53
	v_pk_fma_f32 v[64:65], v[64:65], 0.5, v[54:55] op_sel_hi:[1,0,1] neg_lo:[0,0,1] neg_hi:[0,0,1]
	v_lshlrev_b32_e32 v56, 16, v57
	v_and_b32_e32 v57, 0xffff0000, v57
	v_fma_f32 v35, v35, 0.5, -v32
	v_pk_fma_f32 v[16:17], v[16:17], v[64:65], v[54:55]
	v_lshlrev_b32_e32 v64, 16, v53
	v_and_b32_e32 v33, 0xffff0000, v71
	v_pk_fma_f32 v[58:59], v[58:59], 0.5, v[56:57] op_sel_hi:[1,0,1] neg_lo:[0,0,1] neg_hi:[0,0,1]
	v_mul_f32_e32 v48, v19, v35
	v_fma_f32 v8, v8, 0.5, -v64
	v_pk_fma_f32 v[22:23], v[22:23], v[58:59], v[56:57]
	v_pk_add_f32 v[56:57], v[48:49], v[32:33]
	v_lshlrev_b32_e32 v65, 16, v71
	v_mul_f32_e32 v48, v18, v8
	v_pk_add_f32 v[52:53], v[48:49], v[64:65]
	v_pk_mul_f32 v[58:59], v[10:11], v[56:57]
	v_pk_mul_f32 v[12:13], v[12:13], v[16:17]
	v_pk_mul_f32 v[18:19], v[14:15], v[52:53]
	v_pk_mul_f32 v[54:55], v[12:13], v[12:13]
	v_mov_b32_e32 v35, v16
	v_mov_b32_e32 v37, v17
	v_mov_b32_e32 v16, v58
	v_mov_b32_e32 v17, v18
	v_pk_mul_f32 v[16:17], v[16:17], v[16:17]
	v_add_f32_e32 v8, v54, v55
	v_add_f32_e32 v8, v17, v8
	v_add_f32_e32 v8, v16, v8
	v_lshlrev_b32_e32 v60, 16, v61
	v_and_b32_e32 v61, 0xffff0000, v61
	v_add_f32_dpp v8, v8, v8 quad_perm:[1,0,3,2] row_mask:0xf bank_mask:0xf bound_ctrl:1
	v_pk_fma_f32 v[24:25], v[24:25], 0.5, v[60:61] op_sel_hi:[1,0,1] neg_lo:[0,0,1] neg_hi:[0,0,1]
	ds_write_b128 v183, v[28:31] offset:49664
	v_add_f32_dpp v8, v8, v8 quad_perm:[2,3,0,1] row_mask:0xf bank_mask:0xf bound_ctrl:1
	v_pk_fma_f32 v[60:61], v[26:27], v[24:25], v[60:61]
	v_pk_mul_f32 v[24:25], v[62:63], 1.0 op_sel_hi:[1,0]
	v_add_f32_dpp v8, v8, v8 row_half_mirror row_mask:0xf bank_mask:0xf bound_ctrl:1
	v_pk_mul_f32 v[26:27], v[60:61], 1.0 op_sel_hi:[1,0]
	s_nop 0
	v_add_f32_dpp v8, v8, v8 row_ror:8 row_mask:0xf bank_mask:0xf bound_ctrl:1
	v_cmp_gt_f32_e32 vcc, s96, v8
	v_mul_f32_e32 v16, 0x4f800000, v8
	s_nop 0
	v_cndmask_b32_e32 v8, v8, v16, vcc
	v_sqrt_f32_e32 v16, v8
	s_nop 0
	v_add_u32_e32 v17, -1, v16
	v_fma_f32 v38, -v17, v16, v8
	v_cmp_ge_f32_e64 s[48:49], 0, v38
	v_add_u32_e32 v38, 1, v16
	s_nop 0
	v_cndmask_b32_e64 v17, v16, v17, s[48:49]
	v_fma_f32 v16, -v38, v16, v8
	v_cmp_lt_f32_e64 s[48:49], 0, v16
	s_nop 1
	v_cndmask_b32_e64 v16, v17, v38, s[48:49]
	v_mul_f32_e32 v17, 0x37800000, v16
	v_cndmask_b32_e32 v16, v16, v17, vcc
	v_cmp_class_f32_e32 vcc, v8, v191
	s_nop 1
	v_cndmask_b32_e32 v8, v16, v8, vcc
	v_max_f32_e32 v8, 0x2b8cbccc, v8
	v_div_scale_f32 v16, s[4:5], v8, v8, 1.0
	v_rcp_f32_e32 v17, v16
	s_nop 0
	v_fma_f32 v38, -v16, v17, 1.0
	v_fmac_f32_e32 v17, v38, v17
	v_div_scale_f32 v38, vcc, 1.0, v8, 1.0
	v_mul_f32_e32 v40, v38, v17
	v_fma_f32 v48, -v16, v40, v38
	v_fmac_f32_e32 v40, v48, v17
	v_fma_f32 v16, -v16, v40, v38
	v_div_fmas_f32 v16, v16, v17, v40
	v_div_fixup_f32 v50, v16, v8, 1.0
	v_pk_mul_f32 v[16:17], v[12:13], v[50:51] op_sel_hi:[1,0]
	v_pk_mul_f32 v[18:19], v[18:19], v[50:51]
	v_mov_b32_e32 v38, v16
	v_pk_mul_f32 v[34:35], v[38:39], v[34:35]
	v_pk_mul_f32 v[38:39], v[58:59], v[50:51]
	v_mul_f32_e32 v8, v62, v35
	v_fma_f32 v40, v4, v8, 0
	v_mov_b32_e32 v8, v17
	v_pk_mul_f32 v[12:13], v[8:9], v[36:37]
	v_mov_b32_e32 v9, v41
	v_mul_f32_e32 v4, v63, v13
	v_fmac_f32_e32 v40, v5, v4
	v_pk_fma_f32 v[4:5], v[14:15], v[52:53], s[84:85]
	s_nop 0
	v_mov_b32_e32 v19, v5
	v_pk_mov_b32 v[4:5], v[64:65], v[52:53] op_sel:[1,0]
	s_nop 0
	v_pk_mul_f32 v[36:37], v[18:19], v[4:5]
	v_mov_b32_e32 v19, v38
	v_mul_f32_e32 v4, v60, v37
	v_fmac_f32_e32 v40, v6, v4
	v_pk_fma_f32 v[4:5], v[10:11], v[56:57], s[84:85]
	s_nop 0
	v_mov_b32_e32 v39, v5
	v_pk_mov_b32 v[4:5], v[32:33], v[56:57] op_sel:[1,0]
	ds_write_b128 v183, v[16:19] offset:57856
	v_pk_mul_f32 v[14:15], v[38:39], v[4:5]
	v_mov_b32_e32 v16, v34
	v_mul_f32_e32 v4, v61, v15
	v_fmac_f32_e32 v40, v7, v4
	s_nop 0
	v_mov_b32_e32 v17, v12
	v_add_f32_dpp v4, v40, v40 quad_perm:[1,0,3,2] row_mask:0xf bank_mask:0xf bound_ctrl:1
	v_mov_b32_e32 v18, v36
	v_mov_b32_e32 v19, v14
	v_add_f32_dpp v4, v4, v4 quad_perm:[2,3,0,1] row_mask:0xf bank_mask:0xf bound_ctrl:1
	ds_write_b128 v184, v[16:19] offset:16384
	s_nop 0
	v_add_f32_dpp v8, v4, v4 row_half_mirror row_mask:0xf bank_mask:0xf bound_ctrl:1
	s_nop 0
	s_nop 0
	v_mov_b32_dpp v9, v8 row_ror:8 row_mask:0xf bank_mask:0xf
	s_nop 0
	s_nop 0
	v_mov_b32_e32 v12, v35
	v_mov_b32_e32 v14, v37
	s_nop 0
	s_nop 0
	s_nop 0
	s_nop 0
	s_nop 0
	ds_write_b128 v184, v[12:15] offset:24576
	ds_write_b128 v184, v[24:27] offset:32768
	ds_write_b128 v184, v[20:23] offset:40960
	s_nop 0
	s_nop 0
	s_nop 0
	s_nop 0
	s_nop 0
	s_nop 0
	s_nop 0
	s_nop 0
	s_nop 0
	s_nop 0
	s_nop 0
	s_nop 0
	s_nop 0
	s_nop 0
	s_nop 0
	s_nop 0
	s_nop 0
	s_nop 0
	s_and_b64 s[4:5], s[46:47], s[42:43]
	s_and_saveexec_b64 s[46:47], s[4:5]
	s_cbranch_execz .LBB0_1654
	v_mov_b32_e32 v4, s87
	v_mov_b32_e32 v5, s91
	v_cndmask_b32_e64 v5, v4, v5, s[42:43]
	v_mov_b32_e32 v4, s86
	v_mov_b32_e32 v6, s90
	v_cndmask_b32_e64 v4, v4, v6, s[42:43]
	v_cndmask_b32_e64 v6, v182, v181, s[44:45]
	v_ashrrev_i32_e32 v7, 31, v6
	v_lshl_add_u64 v[4:5], v[4:5], 0, v[6:7]
	v_lshlrev_b64 v[4:5], 7, v[4:5]
	v_add_f32_e32 v6, v8, v9
	v_lshl_add_u64 v[4:5], s[88:89], 0, v[4:5]
	global_store_dword v[4:5], v6, off
	s_branch .LBB0_1654
